# attention loops: counted lgkmcnt waits re-derived per consumer (PV MFMAs no longer wait for all 8 transposed V reads)
# baseline (speedup 1.0000x reference)
; #define SBAR() __builtin_amdgcn_sched_barrier(0)
; __device__ __forceinline__ void finishSM(f32x16& p0, f32x16& p1, float alpha, float& l_reg, bf16x8& pa0, bf16x8& pa1, bf16x8& pa2, bf16x8& pa3) {
; #pragma unroll
;   for (int r = 0; r < 16; ++r) p1[r] = __builtin_amdgcn_exp2f(p1[r]);
;   float ps = 0;
; #pragma unroll
;   for (int r = 0; r < 16; ++r) ps += p0[r];
; #pragma unroll
;   for (int r = 0; r < 16; ++r) ps += p1[r];
;   { auto rr = __builtin_amdgcn_permlane32_swap(__float_as_uint(ps), __float_as_uint(ps), false, false);
;     ps = __uint_as_float(rr[0]) + __uint_as_float(rr[1]); }
;   l_reg = l_reg * alpha + ps;
;     ...
;   PK4(p0, 0, pa0); PK4(p0, 8, pa1); PK4(p1, 0, pa2); PK4(p1, 8, pa3);
;     ...
; }
; template <int DKR, int NQ>
; __device__ __forceinline__ void qkt(f32x16& p0, f32x16& p1, const char* Ks, const char* Krs, const char* Qrs, const bf16x8* qr, int r32, int hi, int lane) {
;   p0 = f32x16{}; p1 = f32x16{};
; #pragma unroll
;   for (int d0 = 0; d0 < 8; ++d0) { int cb = (d0 * 16 + hi * 8) * 2;
;     bf16x8 b0 = *reinterpret_cast<const bf16x8*>(Ks + KSWZ(r32, cb));
;     bf16x8 b1 = *reinterpret_cast<const bf16x8*>(Ks + KSWZ(32 + r32, cb));
;     bf16x8 qf;
;     if (d0 >= 8 - NQ) qf = *reinterpret_cast<const bf16x8*>(Qrs + (d0 - (8 - NQ) + 4) * 1024 + lane * 16); else qf = qr[d0];
;     p0 = __builtin_amdgcn_mfma_f32_32x32x16_bf16(b0, qf, p0, 0, 0, 0);
;     p1 = __builtin_amdgcn_mfma_f32_32x32x16_bf16(b1, qf, p1, 0, 0, 0); }
;   if constexpr (DKR > 0) {
;     SBAR();
; #pragma unroll
;     for (int d0 = 0; d0 < DKR / 16; ++d0) { int cb = (d0 * 16 + hi * 8) * 2;
;       bf16x8 b0 = *reinterpret_cast<const bf16x8*>(Krs + KRSWZ(r32, cb));
;       bf16x8 b1 = *reinterpret_cast<const bf16x8*>(Krs + KRSWZ(32 + r32, cb));
;       bf16x8 qf = *reinterpret_cast<const bf16x8*>(Qrs + d0 * 1024 + lane * 16);
;       p0 = __builtin_amdgcn_mfma_f32_32x32x16_bf16(b0, qf, p0, 0, 0, 0);
;       p1 = __builtin_amdgcn_mfma_f32_32x32x16_bf16(b1, qf, p1, 0, 0, 0); }
;   }
; }
.LBB0_597:
	ds_read_b128 v[64:67], v152 offset:49152
	ds_read_b128 v[176:179], v157 offset:49152
	s_waitcnt lgkmcnt(1)
	v_mfma_f32_32x32x16_bf16 v[80:95], v[64:67], v[104:107], 0
	ds_read_b128 v[64:67], v152 offset:57344
	s_waitcnt lgkmcnt(1)
	v_mfma_f32_32x32x16_bf16 v[80:95], v[176:179], v[100:103], v[80:95]
	ds_read_b128 v[176:179], v157 offset:57344
	s_waitcnt lgkmcnt(1)
	v_mfma_f32_32x32x16_bf16 v[64:79], v[64:67], v[104:107], 0
	s_waitcnt lgkmcnt(0)
	v_mfma_f32_32x32x16_bf16 v[64:79], v[176:179], v[100:103], v[64:79]
	ds_read_b128 v[176:179], v158 offset:49152
	s_waitcnt lgkmcnt(0)
	v_mfma_f32_32x32x16_bf16 v[80:95], v[176:179], v[96:99], v[80:95]
	ds_read_b128 v[176:179], v158 offset:57344
	s_waitcnt lgkmcnt(0)
	v_mfma_f32_32x32x16_bf16 v[64:79], v[176:179], v[96:99], v[64:79]
	ds_read_b128 v[176:179], v159 offset:49152
	ds_read_b128 v[190:193], v148 offset:4096
	s_waitcnt lgkmcnt(0)
	v_mfma_f32_32x32x16_bf16 v[80:95], v[176:179], v[190:193], v[80:95]
	ds_read_b128 v[176:179], v159 offset:57344
	s_waitcnt lgkmcnt(0)
	v_mfma_f32_32x32x16_bf16 v[64:79], v[176:179], v[190:193], v[64:79]
	ds_read_b128 v[176:179], v160 offset:49152
	ds_read_b128 v[190:193], v148 offset:5120
	s_waitcnt lgkmcnt(0)
	v_mfma_f32_32x32x16_bf16 v[80:95], v[176:179], v[190:193], v[80:95]
	ds_read_b128 v[176:179], v160 offset:57344
	s_waitcnt lgkmcnt(0)
	v_mfma_f32_32x32x16_bf16 v[64:79], v[176:179], v[190:193], v[64:79]
	ds_read_b128 v[176:179], v161 offset:49152
	ds_read_b128 v[190:193], v148 offset:6144
	s_waitcnt lgkmcnt(0)
	v_mfma_f32_32x32x16_bf16 v[80:95], v[176:179], v[190:193], v[80:95]
	ds_read_b128 v[176:179], v161 offset:57344
	s_waitcnt lgkmcnt(0)
	v_mfma_f32_32x32x16_bf16 v[64:79], v[176:179], v[190:193], v[64:79]
	ds_read_b128 v[176:179], v162 offset:49152
	ds_read_b128 v[190:193], v148 offset:7168
	s_waitcnt lgkmcnt(0)
	v_mfma_f32_32x32x16_bf16 v[80:95], v[176:179], v[190:193], v[80:95]
	ds_read_b128 v[176:179], v162 offset:57344
	s_waitcnt lgkmcnt(0)
	v_mfma_f32_32x32x16_bf16 v[64:79], v[176:179], v[190:193], v[64:79]
	ds_read_b128 v[176:179], v163 offset:49152
	ds_read_b128 v[190:193], v148 offset:8192
	s_waitcnt lgkmcnt(0)
	v_mfma_f32_32x32x16_bf16 v[80:95], v[176:179], v[190:193], v[80:95]
	ds_read_b128 v[176:179], v163 offset:57344
	s_waitcnt lgkmcnt(0)
	v_mfma_f32_32x32x16_bf16 v[64:79], v[176:179], v[190:193], v[64:79]
	s_add_i32 s0, 0, 0x12800
	v_add_u32_e32 v177, s0, v164
	ds_read_b128 v[178:181], v177
	ds_read_b128 v[190:193], v177 offset:4096
	ds_read_b128 v[194:197], v148
	v_add_u32_e32 v176, s0, v166
	v_exp_f32_e32 v120, v120
	v_exp_f32_e32 v121, v121
	v_exp_f32_e32 v140, v116
	s_waitcnt lgkmcnt(0)
	v_mfma_f32_32x32x16_bf16 v[80:95], v[178:181], v[194:197], v[80:95]
	v_exp_f32_e32 v117, v117
	v_exp_f32_e32 v182, v114
	v_exp_f32_e32 v188, v115
	v_exp_f32_e32 v122, v122
	v_exp_f32_e32 v123, v123
	v_mfma_f32_32x32x16_bf16 v[64:79], v[190:193], v[194:197], v[64:79]
	ds_read_b128 v[178:181], v176
	ds_read_b128 v[190:193], v176 offset:4096
	ds_read_b128 v[194:197], v148 offset:1024
	s_waitcnt lgkmcnt(0)
	v_mfma_f32_32x32x16_bf16 v[80:95], v[178:181], v[194:197], v[80:95]
	v_add_u32_e32 v178, s0, v168
	v_add_u32_e32 v179, s0, v170
	v_mfma_f32_32x32x16_bf16 v[64:79], v[190:193], v[194:197], v[64:79]
	ds_read_b128 v[190:193], v178
	ds_read_b128 v[194:197], v178 offset:4096
	ds_read_b128 v[198:201], v148 offset:2048
	s_waitcnt lgkmcnt(0)
	v_mfma_f32_32x32x16_bf16 v[80:95], v[190:193], v[198:201], v[80:95]
	v_mfma_f32_32x32x16_bf16 v[64:79], v[194:197], v[198:201], v[64:79]
	ds_read_b128 v[190:193], v179
	ds_read_b128 v[194:197], v179 offset:4096
	ds_read_b128 v[198:201], v148 offset:3072
	s_waitcnt lgkmcnt(0)
	v_mfma_f32_32x32x16_bf16 v[80:95], v[190:193], v[198:201], v[80:95]
	v_exp_f32_e32 v192, v108
	v_add_f32_e32 v108, 0, v185
	v_add_f32_e32 v108, v187, v108
	v_add_f32_e32 v108, v183, v108
	v_add_f32_e32 v108, v186, v108
	v_add_f32_e32 v108, v142, v108
	v_add_f32_e32 v108, v184, v108
	v_add_f32_e32 v108, v141, v108
	v_add_f32_e32 v108, v143, v108
	v_add_f32_e32 v108, v129, v108
	v_add_f32_e32 v108, v131, v108
	v_add_f32_e32 v108, v127, v108
	v_add_f32_e32 v108, v130, v108
	v_add_f32_e32 v108, v125, v108
	v_add_f32_e32 v108, v128, v108
	v_add_f32_e32 v108, v124, v108
	v_add_f32_e32 v108, v126, v108
	v_add_f32_e32 v108, v120, v108
	v_add_f32_e32 v108, v121, v108
	v_exp_f32_e32 v190, v112
	v_add_f32_e32 v108, v140, v108
	v_exp_f32_e32 v191, v113
	v_add_f32_e32 v108, v117, v108
	v_add_f32_e32 v108, v182, v108
	v_exp_f32_e32 v193, v109
	v_add_f32_e32 v108, v188, v108
	v_add_f32_e32 v108, v190, v108
	v_add_f32_e32 v108, v191, v108
	v_mfma_f32_32x32x16_bf16 v[64:79], v[194:197], v[198:201], v[64:79]
	v_exp_f32_e32 v194, v118
	v_add_f32_e32 v108, v192, v108
	v_exp_f32_e32 v195, v119
	v_add_f32_e32 v108, v193, v108
	v_exp_f32_e32 v196, v110
	v_add_f32_e32 v108, v122, v108
	v_exp_f32_e32 v197, v111
	v_add_f32_e32 v108, v123, v108
	v_add_f32_e32 v108, v194, v108
	v_add_f32_e32 v108, v195, v108
	v_add_f32_e32 v108, v196, v108
	v_add_f32_e32 v180, v197, v108
	v_mov_b32_e32 v181, v180
	s_nop 1
	v_permlane32_swap_b32_e32 v180, v181
	v_cvt_pk_bf16_f32 v108, v185, v187
	v_cvt_pk_bf16_f32 v109, v183, v186
	v_cvt_pk_bf16_f32 v110, v142, v184
	v_cvt_pk_bf16_f32 v111, v141, v143
	v_cvt_pk_bf16_f32 v112, v129, v131
	v_cvt_pk_bf16_f32 v113, v127, v130
	v_cvt_pk_bf16_f32 v114, v125, v128
	v_cvt_pk_bf16_f32 v115, v124, v126
	v_cvt_pk_bf16_f32 v116, v120, v121
	v_cvt_pk_bf16_f32 v117, v140, v117
	v_cvt_pk_bf16_f32 v118, v182, v188
	v_cvt_pk_bf16_f32 v119, v190, v191
	v_cvt_pk_bf16_f32 v120, v192, v193
	v_cvt_pk_bf16_f32 v121, v122, v123
	v_cvt_pk_bf16_f32 v122, v194, v195
; __device__ __forceinline__ void pv_sm(f32x16* o, int vb, bf16x8 pa0, bf16x8 pa1, bf16x8 pa2, bf16x8 pa3, f32x16& p0, f32x16& p1, float& m_reg, float& mn, float& alpha, const float SCALE) {
;   const float C = SCALE * 1.4426950408889634f;
;   pv_one<0>(o[0], vb, pa0, pa1, pa2, pa3);
;   float pmax = p0[0];
; #pragma unroll
;   for (int r = 1; r < 16; ++r) pmax = fmaxf(pmax, p0[r]);
;   pv_one<1>(o[1], vb, pa0, pa1, pa2, pa3);
; #pragma unroll
;   for (int r = 0; r < 16; ++r) pmax = fmaxf(pmax, p1[r]);
;   { auto rr = __builtin_amdgcn_permlane32_swap(__float_as_uint(pmax), __float_as_uint(pmax), false, false);
;     pmax = fmaxf(__uint_as_float(rr[0]), __uint_as_float(rr[1])); }
;   if (__builtin_expect(__all(pmax - m_reg <= THR / SCALE), 1)) { mn = m_reg; alpha = 1.f; }
;   else { mn = fmaxf(m_reg, pmax); alpha = __builtin_amdgcn_exp2f((m_reg - mn) * C); m_reg = mn; }
;   const float mnC = -mn * C;
;   pv_one<2>(o[2], vb, pa0, pa1, pa2, pa3);
; #pragma unroll
;   for (int r = 0; r < 16; ++r) p0[r] = fmaf(p0[r], C, mnC);
; #pragma unroll
;   for (int r = 0; r < 16; ++r) p1[r] = fmaf(p1[r], C, mnC);
;   pv_one<3>(o[3], vb, pa0, pa1, pa2, pa3);
; #pragma unroll
;   for (int r = 0; r < 16; ++r) p0[r] = __builtin_amdgcn_exp2f(p0[r]);
; }
	v_cvt_pk_bf16_f32 v123, v196, v197
	s_nop 0
	v_permlane32_swap_b32_e32 v108, v110
	v_permlane32_swap_b32_e32 v109, v111
	v_permlane32_swap_b32_e32 v112, v114
	v_permlane32_swap_b32_e32 v113, v115
	v_permlane32_swap_b32_e32 v116, v118
	v_permlane32_swap_b32_e32 v117, v119
	v_permlane32_swap_b32_e32 v120, v122
	v_permlane32_swap_b32_e32 v121, v123
	v_lshl_add_u64 v[140:141], s[26:27], 0, v[136:137]
	s_mov_b32 s0, 0x6e40000
	v_add_co_u32_e32 v124, vcc, s0, v140
	s_mov_b32 s0, 0x6e50000
	s_nop 0
	v_addc_co_u32_e32 v125, vcc, 0, v141, vcc
	v_add_co_u32_e32 v128, vcc, s0, v140
	s_mov_b32 s0, 0x4a40000
	s_nop 0
	v_addc_co_u32_e32 v129, vcc, 0, v141, vcc
	v_add_co_u32_e32 v142, vcc, s0, v140
	s_mov_b32 s0, 0x4a50000
	s_nop 0
	v_addc_co_u32_e32 v143, vcc, 0, v141, vcc
	v_add_co_u32_e32 v182, vcc, s0, v140
	global_load_dwordx4 v[124:127], v[124:125], off
	s_nop 0
	global_load_dwordx4 v[128:131], v[128:129], off
	v_addc_co_u32_e32 v183, vcc, 0, v141, vcc
	global_load_dwordx4 v[184:187], v[142:143], off
	global_load_dwordx4 v[190:193], v[182:183], off
	v_lshl_add_u64 v[142:143], s[26:27], 0, v[138:139]
	s_mov_b32 s0, 0x11504000
	v_add_co_u32_e32 v182, vcc, s0, v142
	s_nop 1
	v_addc_co_u32_e32 v183, vcc, 0, v143, vcc
	global_load_dwordx4 v[194:197], v[182:183], off
	ds_read_b64_tr_b16 v[198:199], v151 offset:0
	ds_read_b64_tr_b16 v[200:201], v151 offset:0x800
	ds_read_b64_tr_b16 v[202:203], v151 offset:0x1000
	ds_read_b64_tr_b16 v[204:205], v151 offset:0x1800
	ds_read_b64_tr_b16 v[206:207], v151 offset:0x2000
	ds_read_b64_tr_b16 v[208:209], v151 offset:0x2800
	ds_read_b64_tr_b16 v[214:215], v151 offset:0x3000
	ds_read_b64_tr_b16 v[216:217], v151 offset:0x3800
	s_nop 0
	s_waitcnt lgkmcnt(6)
	v_mfma_f32_32x32x16_bf16 v[0:15], v[108:111], v[198:201], v[0:15]
	ds_read_b64_tr_b16 v[198:199], v151 offset:0x200
	ds_read_b64_tr_b16 v[200:201], v151 offset:0xa00
	v_max_f32_e32 v182, v81, v81
	v_max_f32_e32 v183, v80, v80
	v_max_f32_e32 v182, v183, v182
	v_max3_f32 v182, v182, v82, v83
	v_max3_f32 v182, v182, v84, v85
	s_waitcnt lgkmcnt(6)
	v_mfma_f32_32x32x16_bf16 v[0:15], v[112:115], v[202:205], v[0:15]
	ds_read_b64_tr_b16 v[202:203], v151 offset:0x1200
	ds_read_b64_tr_b16 v[204:205], v151 offset:0x1a00
	v_max3_f32 v182, v182, v86, v87
	v_max3_f32 v182, v182, v88, v89
	v_max3_f32 v182, v182, v90, v91
	v_max3_f32 v182, v182, v92, v93
	v_max3_f32 v182, v182, v94, v95
	s_waitcnt lgkmcnt(6)
	v_mfma_f32_32x32x16_bf16 v[0:15], v[116:119], v[206:209], v[0:15]
	ds_read_b64_tr_b16 v[206:207], v151 offset:0x2200
	ds_read_b64_tr_b16 v[208:209], v151 offset:0x2a00
	s_waitcnt lgkmcnt(6)
	v_mfma_f32_32x32x16_bf16 v[0:15], v[120:123], v[214:217], v[0:15]
	ds_read_b64_tr_b16 v[214:215], v151 offset:0x3200
	ds_read_b64_tr_b16 v[216:217], v151 offset:0x3a00
	s_waitcnt lgkmcnt(6)
	v_mfma_f32_32x32x16_bf16 v[48:63], v[108:111], v[198:201], v[48:63]
	v_max3_f32 v182, v182, v64, v65
	v_max3_f32 v182, v182, v66, v67
	v_max3_f32 v182, v182, v68, v69
	v_max3_f32 v182, v182, v70, v71
	v_max3_f32 v182, v182, v72, v73
	v_max3_f32 v182, v182, v74, v75
	v_max3_f32 v182, v182, v76, v77
	s_waitcnt lgkmcnt(4)
	v_mfma_f32_32x32x16_bf16 v[48:63], v[112:115], v[202:205], v[48:63]
	v_max3_f32 v182, v182, v78, v79
	v_mov_b32_e32 v183, v182
	s_nop 1
	v_permlane32_swap_b32_e32 v182, v183
	ds_read_b64_tr_b16 v[198:199], v151 offset:0x400
	v_max_f32_e32 v183, v183, v183
	v_max_f32_e32 v182, v182, v182
	s_waitcnt lgkmcnt(3)
	v_mfma_f32_32x32x16_bf16 v[48:63], v[116:119], v[206:209], v[48:63]
	ds_read_b64_tr_b16 v[200:201], v151 offset:0xc00
	v_max_f32_e32 v182, v182, v183
	v_max_f32_e32 v183, v175, v175
	ds_read_b64_tr_b16 v[202:203], v151 offset:0x1400
	v_max_f32_e32 v183, v183, v182
	ds_read_b64_tr_b16 v[204:205], v151 offset:0x1c00
	v_sub_f32_e32 v188, v182, v175
	s_waitcnt lgkmcnt(4)
	v_mfma_f32_32x32x16_bf16 v[48:63], v[120:123], v[214:217], v[48:63]
	v_sub_f32_e32 v182, v175, v183
	ds_read_b64_tr_b16 v[206:207], v151 offset:0x2400
	v_mul_f32_e32 v182, 0x3dd53b94, v182
	ds_read_b64_tr_b16 v[208:209], v151 offset:0x2c00
	v_exp_f32_e32 v182, v182
	ds_read_b64_tr_b16 v[214:215], v151 offset:0x3400
	v_cmp_ge_f32_e32 vcc, s82, v188
	ds_read_b64_tr_b16 v[216:217], v151 offset:0x3c00
	s_cmp_eq_u64 vcc, exec
	s_cselect_b64 s[4:5], -1, 0
	v_cndmask_b32_e64 v182, v182, 1.0, s[4:5]
	s_waitcnt lgkmcnt(6)
	v_mfma_f32_32x32x16_bf16 v[32:47], v[108:111], v[198:201], v[32:47]
	ds_read_b64_tr_b16 v[198:199], v151 offset:0x600
	ds_read_b64_tr_b16 v[200:201], v151 offset:0xe00
	s_waitcnt lgkmcnt(6)
	v_mfma_f32_32x32x16_bf16 v[32:47], v[112:115], v[202:205], v[32:47]
	ds_read_b64_tr_b16 v[202:203], v151 offset:0x1600
	ds_read_b64_tr_b16 v[204:205], v151 offset:0x1e00
	s_waitcnt lgkmcnt(6)
	v_mfma_f32_32x32x16_bf16 v[32:47], v[116:119], v[206:209], v[32:47]
	ds_read_b64_tr_b16 v[206:207], v151 offset:0x2600
	ds_read_b64_tr_b16 v[208:209], v151 offset:0x2e00
	s_waitcnt lgkmcnt(6)
	v_mfma_f32_32x32x16_bf16 v[32:47], v[120:123], v[214:217], v[32:47]
	ds_read_b64_tr_b16 v[214:215], v151 offset:0x3600
	ds_read_b64_tr_b16 v[216:217], v151 offset:0x3e00
	s_waitcnt lgkmcnt(6)
	v_mfma_f32_32x32x16_bf16 v[16:31], v[108:111], v[198:201], v[16:31]
	s_waitcnt lgkmcnt(0)
	s_barrier
	s_waitcnt vmcnt(0)
	v_add_u32_e32 v108, 0x10800, v173
	v_cmp_gt_f32_e32 vcc, 1.0, v182
	s_waitcnt vmcnt(4)
	ds_write_b128 v155, v[124:127]
	s_waitcnt vmcnt(3)
	ds_write_b128 v156, v[128:131]
	s_waitcnt vmcnt(2)
	ds_write_b128 v153, v[184:187] offset:32768
	s_waitcnt vmcnt(1)
	ds_write_b128 v154, v[190:193] offset:32768
	v_mfma_f32_32x32x16_bf16 v[16:31], v[112:115], v[202:205], v[16:31]
	s_waitcnt vmcnt(0)
	ds_write_b128 v108, v[194:197]
	v_mfma_f32_32x32x16_bf16 v[16:31], v[116:119], v[206:209], v[16:31]
	v_mfma_f32_32x32x16_bf16 v[16:31], v[120:123], v[214:217], v[16:31]
	s_cbranch_vccz .LBB0_601
; #define SBAR() __builtin_amdgcn_sched_barrier(0)
; #define SWAIT() do { if constexpr (SD == 1) asm volatile("s_waitcnt vmcnt(0)" ::: "memory"); else asm volatile("s_waitcnt vmcnt(4)" ::: "memory"); } while (0)
; #define RESC(a) do { if (__any((a) < 1.f)) { if (hi == 0) al_l[r32] = (a); asm volatile("s_waitcnt lgkmcnt(0)" ::: "memory"); \
;     _Pragma("unroll") for (int d = 0; d < 4; ++d) _Pragma("unroll") for (int r = 0; r < 16; ++r) o[d][r] *= al_l[crow(r, hi)]; } } while (0)
; __device__ __forceinline__ void pv_sm(f32x16* o, int vb, bf16x8 pa0, bf16x8 pa1, bf16x8 pa2, bf16x8 pa3, f32x16& p0, f32x16& p1, float& m_reg, float& mn, float& alpha, const float SCALE) {
;     ...
;   for (int r = 0; r < 16; ++r) p0[r] = fmaf(p0[r], C, mnC);
; #pragma unroll
;   for (int r = 0; r < 16; ++r) p1[r] = fmaf(p1[r], C, mnC);
;   pv_one<3>(o[3], vb, pa0, pa1, pa2, pa3);
; #pragma unroll
;   for (int r = 0; r < 16; ++r) p0[r] = __builtin_amdgcn_exp2f(p0[r]);
; template <int DKR, int LDQ, int LDK, int LDV, int LDO> ...
;     ...
;   f32x16 pA0, pA1, pB0, pB1; float mnA, mnB, alA, alB; bf16x8 pa0, pa1, pa2, pa3; const int NT = seq / KVBLK;
;   constexpr int SE = 0, SO = SD - 1;
;   SLOAD(SE, 0); asm volatile("s_waitcnt vmcnt(0)" ::: "memory"); SWRITE(0, SE); __syncthreads();
;   qkt<DKR, NQ>(pA0, pA1, K_lds, KR_lds, QR_lds, qr, r32, hi, lane); partialSM(pA0, pA1, m_reg, mnA, alA, SCALE);
;   SLOAD(SO, KVBLK); if constexpr (SD == 2) { if (2 < NT) SLOAD(SE, 2 * KVBLK); }
;   SWAIT(); SWRITE(1, SO); __syncthreads();
;   for (int j = 1; j + 1 < NT; j += 2) {
;     SBAR(); qkt<DKR, NQ>(pB0, pB1, K_lds + SHM_K, KR_lds + SHM_KR, QR_lds, qr, r32, hi, lane);
;     finishSM(pA0, pA1, alA, l_reg, pa0, pa1, pa2, pa3); SBAR();
;     SLOAD(SO, (j + SD) * KVBLK); SBAR();
;     pv_sm(o, vb0, pa0, pa1, pa2, pa3, pB0, pB1, m_reg, mnB, alB, SCALE);
;     __syncthreads(); SWAIT(); SWRITE(0, SE);
;     RESC(alB); __syncthreads();
;     SBAR(); qkt<DKR, NQ>(pA0, pA1, K_lds, KR_lds, QR_lds, qr, r32, hi, lane);
	s_and_saveexec_b64 s[0:1], s[2:3]
	ds_write_b32 v147, v182 offset:128
	s_or_b64 exec, exec, s[0:1]
	s_waitcnt lgkmcnt(0)
	v_add_u32_e32 v120, v135, v132
	ds_read_b128 v[108:111], v120 offset:224
	ds_read_b128 v[112:115], v120 offset:192
	ds_read_b128 v[116:119], v120 offset:160
	ds_read_b128 v[120:123], v120 offset:128
	s_waitcnt lgkmcnt(3)
	v_pk_mul_f32 v[12:13], v[12:13], v[108:109]
	s_waitcnt lgkmcnt(2)
	v_pk_mul_f32 v[8:9], v[8:9], v[112:113]
	s_waitcnt lgkmcnt(1)
	v_pk_mul_f32 v[4:5], v[4:5], v[116:117]
	v_pk_mul_f32 v[14:15], v[14:15], v[110:111]
	v_pk_mul_f32 v[10:11], v[10:11], v[114:115]
	v_pk_mul_f32 v[6:7], v[6:7], v[118:119]
	s_waitcnt lgkmcnt(0)
	v_pk_mul_f32 v[2:3], v[2:3], v[122:123]
	v_pk_mul_f32 v[0:1], v[0:1], v[120:121]
	v_pk_mul_f32 v[60:61], v[60:61], v[108:109]
	v_pk_mul_f32 v[56:57], v[56:57], v[112:113]
	v_pk_mul_f32 v[52:53], v[52:53], v[116:117]
	v_pk_mul_f32 v[62:63], v[62:63], v[110:111]
	v_pk_mul_f32 v[58:59], v[58:59], v[114:115]
	v_pk_mul_f32 v[54:55], v[54:55], v[118:119]
	v_pk_mul_f32 v[50:51], v[50:51], v[122:123]
	v_pk_mul_f32 v[48:49], v[48:49], v[120:121]
	v_pk_mul_f32 v[44:45], v[44:45], v[108:109]
	v_pk_mul_f32 v[40:41], v[40:41], v[112:113]
	v_pk_mul_f32 v[36:37], v[36:37], v[116:117]
	v_pk_mul_f32 v[46:47], v[46:47], v[110:111]
	v_pk_mul_f32 v[42:43], v[42:43], v[114:115]
	v_pk_mul_f32 v[38:39], v[38:39], v[118:119]
	v_pk_mul_f32 v[34:35], v[34:35], v[122:123]
	v_pk_mul_f32 v[32:33], v[32:33], v[120:121]
	v_pk_mul_f32 v[28:29], v[28:29], v[108:109]
	v_pk_mul_f32 v[24:25], v[24:25], v[112:113]
	v_pk_mul_f32 v[20:21], v[20:21], v[116:117]
	v_pk_mul_f32 v[30:31], v[30:31], v[110:111]
	v_pk_mul_f32 v[26:27], v[26:27], v[114:115]
	v_pk_mul_f32 v[22:23], v[22:23], v[118:119]
	v_pk_mul_f32 v[18:19], v[18:19], v[122:123]
	v_pk_mul_f32 v[16:17], v[16:17], v[120:121]
.LBB0_601:
	v_cndmask_b32_e64 v175, v183, v175, s[4:5]
	v_mul_f32_e32 v124, 0xbdd53b94, v175
	v_fmamk_f32 v80, v80, 0x3dd53b94, v124
	v_fmamk_f32 v81, v81, 0x3dd53b94, v124
	v_fmamk_f32 v82, v82, 0x3dd53b94, v124
	v_fmamk_f32 v83, v83, 0x3dd53b94, v124
	v_fmamk_f32 v84, v84, 0x3dd53b94, v124
	v_fmamk_f32 v85, v85, 0x3dd53b94, v124
	v_fmamk_f32 v86, v86, 0x3dd53b94, v124
	v_fmamk_f32 v87, v87, 0x3dd53b94, v124
	v_fmamk_f32 v88, v88, 0x3dd53b94, v124
	v_fmamk_f32 v89, v89, 0x3dd53b94, v124
	v_fmamk_f32 v90, v90, 0x3dd53b94, v124
	v_fmamk_f32 v91, v91, 0x3dd53b94, v124
	v_fmamk_f32 v92, v92, 0x3dd53b94, v124
	v_fmamk_f32 v93, v93, 0x3dd53b94, v124
	v_fmamk_f32 v94, v94, 0x3dd53b94, v124
	v_fmamk_f32 v95, v95, 0x3dd53b94, v124
	v_fmamk_f32 v188, v64, 0x3dd53b94, v124
	v_fmamk_f32 v190, v77, 0x3dd53b94, v124
	v_fmamk_f32 v130, v65, 0x3dd53b94, v124
	v_fmamk_f32 v131, v66, 0x3dd53b94, v124
	v_fmamk_f32 v183, v67, 0x3dd53b94, v124
	v_fmamk_f32 v184, v68, 0x3dd53b94, v124
	v_fmamk_f32 v185, v69, 0x3dd53b94, v124
	v_fmamk_f32 v186, v70, 0x3dd53b94, v124
	v_fmamk_f32 v187, v71, 0x3dd53b94, v124
	v_fmamk_f32 v125, v72, 0x3dd53b94, v124
	v_fmamk_f32 v126, v73, 0x3dd53b94, v124
	v_fmamk_f32 v127, v74, 0x3dd53b94, v124
	v_fmamk_f32 v128, v75, 0x3dd53b94, v124
	v_fmamk_f32 v129, v76, 0x3dd53b94, v124
	v_exp_f32_e32 v108, v80
	v_exp_f32_e32 v123, v81
	v_exp_f32_e32 v109, v82
	v_exp_f32_e32 v122, v83
	v_exp_f32_e32 v110, v84
	v_exp_f32_e32 v121, v85
	v_exp_f32_e32 v111, v86
	v_exp_f32_e32 v120, v87
	v_exp_f32_e32 v112, v88
	v_exp_f32_e32 v119, v89
	v_exp_f32_e32 v113, v90
	v_exp_f32_e32 v118, v91
	v_exp_f32_e32 v114, v92
	v_exp_f32_e32 v117, v93
	v_exp_f32_e32 v115, v94
	v_exp_f32_e32 v116, v95
	v_fmamk_f32 v191, v78, 0x3dd53b94, v124
	v_fmac_f32_e32 v124, 0x3dd53b94, v79
	s_waitcnt lgkmcnt(0)
	s_barrier
	ds_read_b128 v[64:67], v152 offset:32768
	ds_read_b128 v[192:195], v157 offset:32768
	s_waitcnt lgkmcnt(1)
	v_mfma_f32_32x32x16_bf16 v[80:95], v[64:67], v[104:107], 0
	ds_read_b128 v[64:67], v152 offset:40960
	s_waitcnt lgkmcnt(1)
	v_mfma_f32_32x32x16_bf16 v[80:95], v[192:195], v[100:103], v[80:95]
	ds_read_b128 v[192:195], v157 offset:40960
	s_waitcnt lgkmcnt(1)
	v_mfma_f32_32x32x16_bf16 v[64:79], v[64:67], v[104:107], 0
	s_waitcnt lgkmcnt(0)
	v_mfma_f32_32x32x16_bf16 v[64:79], v[192:195], v[100:103], v[64:79]
	ds_read_b128 v[192:195], v158 offset:32768
	s_waitcnt lgkmcnt(0)
	v_mfma_f32_32x32x16_bf16 v[80:95], v[192:195], v[96:99], v[80:95]
	ds_read_b128 v[192:195], v158 offset:40960
	s_waitcnt lgkmcnt(0)
	v_mfma_f32_32x32x16_bf16 v[64:79], v[192:195], v[96:99], v[64:79]
	ds_read_b128 v[192:195], v159 offset:32768
	ds_read_b128 v[196:199], v148 offset:4096
	s_waitcnt lgkmcnt(0)
	v_mfma_f32_32x32x16_bf16 v[80:95], v[192:195], v[196:199], v[80:95]
	ds_read_b128 v[192:195], v159 offset:40960
	s_waitcnt lgkmcnt(0)
	v_mfma_f32_32x32x16_bf16 v[64:79], v[192:195], v[196:199], v[64:79]
	ds_read_b128 v[192:195], v160 offset:32768
	ds_read_b128 v[196:199], v148 offset:5120
	s_waitcnt lgkmcnt(0)
	v_mfma_f32_32x32x16_bf16 v[80:95], v[192:195], v[196:199], v[80:95]
	ds_read_b128 v[192:195], v160 offset:40960
	s_waitcnt lgkmcnt(0)
	v_mfma_f32_32x32x16_bf16 v[64:79], v[192:195], v[196:199], v[64:79]
	ds_read_b128 v[192:195], v161 offset:32768
	ds_read_b128 v[196:199], v148 offset:6144
	s_waitcnt lgkmcnt(0)
	v_mfma_f32_32x32x16_bf16 v[80:95], v[192:195], v[196:199], v[80:95]
	ds_read_b128 v[192:195], v161 offset:40960
	s_waitcnt lgkmcnt(0)
	v_mfma_f32_32x32x16_bf16 v[64:79], v[192:195], v[196:199], v[64:79]
	ds_read_b128 v[192:195], v162 offset:32768
	ds_read_b128 v[196:199], v148 offset:7168
	s_waitcnt lgkmcnt(0)
	v_mfma_f32_32x32x16_bf16 v[80:95], v[192:195], v[196:199], v[80:95]
	ds_read_b128 v[192:195], v162 offset:40960
	s_waitcnt lgkmcnt(0)
; #define SBAR() __builtin_amdgcn_sched_barrier(0)
; __device__ __forceinline__ void finishSM(f32x16& p0, f32x16& p1, float alpha, float& l_reg, bf16x8& pa0, bf16x8& pa1, bf16x8& pa2, bf16x8& pa3) {
; #pragma unroll
;   for (int r = 0; r < 16; ++r) p1[r] = __builtin_amdgcn_exp2f(p1[r]);
;   float ps = 0;
; #pragma unroll
;   for (int r = 0; r < 16; ++r) ps += p0[r];
; #pragma unroll
;   for (int r = 0; r < 16; ++r) ps += p1[r];
;   { auto rr = __builtin_amdgcn_permlane32_swap(__float_as_uint(ps), __float_as_uint(ps), false, false);
;     ps = __uint_as_float(rr[0]) + __uint_as_float(rr[1]); }
;   l_reg = l_reg * alpha + ps;
;     ...
;   PK4(p0, 0, pa0); PK4(p0, 8, pa1); PK4(p1, 0, pa2); PK4(p1, 8, pa3);
;     ...
; }
; template <int DKR, int NQ>
; __device__ __forceinline__ void qkt(f32x16& p0, f32x16& p1, const char* Ks, const char* Krs, const char* Qrs, const bf16x8* qr, int r32, int hi, int lane) {
;   p0 = f32x16{}; p1 = f32x16{};
; #pragma unroll
;   for (int d0 = 0; d0 < 8; ++d0) { int cb = (d0 * 16 + hi * 8) * 2;
;     bf16x8 b0 = *reinterpret_cast<const bf16x8*>(Ks + KSWZ(r32, cb));
;     bf16x8 b1 = *reinterpret_cast<const bf16x8*>(Ks + KSWZ(32 + r32, cb));
;     bf16x8 qf;
;     if (d0 >= 8 - NQ) qf = *reinterpret_cast<const bf16x8*>(Qrs + (d0 - (8 - NQ) + 4) * 1024 + lane * 16); else qf = qr[d0];
;     p0 = __builtin_amdgcn_mfma_f32_32x32x16_bf16(b0, qf, p0, 0, 0, 0);
;     p1 = __builtin_amdgcn_mfma_f32_32x32x16_bf16(b1, qf, p1, 0, 0, 0); }
;   if constexpr (DKR > 0) {
;     SBAR();
; #pragma unroll
;     for (int d0 = 0; d0 < DKR / 16; ++d0) { int cb = (d0 * 16 + hi * 8) * 2;
;       bf16x8 b0 = *reinterpret_cast<const bf16x8*>(Krs + KRSWZ(r32, cb));
;       bf16x8 b1 = *reinterpret_cast<const bf16x8*>(Krs + KRSWZ(32 + r32, cb));
;       bf16x8 qf = *reinterpret_cast<const bf16x8*>(Qrs + d0 * 1024 + lane * 16);
;       p0 = __builtin_amdgcn_mfma_f32_32x32x16_bf16(b0, qf, p0, 0, 0, 0);
;       p1 = __builtin_amdgcn_mfma_f32_32x32x16_bf16(b1, qf, p1, 0, 0, 0); }
;   }
; }
	v_mfma_f32_32x32x16_bf16 v[64:79], v[192:195], v[196:199], v[64:79]
	ds_read_b128 v[192:195], v163 offset:32768
	ds_read_b128 v[196:199], v148 offset:8192
	s_waitcnt lgkmcnt(0)
	v_mfma_f32_32x32x16_bf16 v[80:95], v[192:195], v[196:199], v[80:95]
	ds_read_b128 v[192:195], v163 offset:40960
	s_waitcnt lgkmcnt(0)
	v_mfma_f32_32x32x16_bf16 v[64:79], v[192:195], v[196:199], v[64:79]
	ds_read_b128 v[192:195], v165
	ds_read_b128 v[196:199], v165 offset:4096
	ds_read_b128 v[200:203], v148
	v_exp_f32_e32 v130, v130
	v_exp_f32_e32 v131, v131
	v_exp_f32_e32 v183, v183
	v_exp_f32_e32 v184, v184
	s_waitcnt lgkmcnt(0)
	v_mfma_f32_32x32x16_bf16 v[80:95], v[192:195], v[200:203], v[80:95]
	v_exp_f32_e32 v185, v185
	v_exp_f32_e32 v186, v186
	v_exp_f32_e32 v187, v187
	v_exp_f32_e32 v125, v125
	v_exp_f32_e32 v126, v126
	v_exp_f32_e32 v127, v127
	v_exp_f32_e32 v128, v128
	v_mfma_f32_32x32x16_bf16 v[64:79], v[196:199], v[200:203], v[64:79]
	ds_read_b128 v[192:195], v167
	ds_read_b128 v[196:199], v167 offset:4096
	ds_read_b128 v[200:203], v148 offset:1024
	v_exp_f32_e32 v129, v129
	v_exp_f32_e32 v191, v191
	v_exp_f32_e32 v124, v124
	s_waitcnt lgkmcnt(0)
	v_mfma_f32_32x32x16_bf16 v[80:95], v[192:195], v[200:203], v[80:95]
	v_mfma_f32_32x32x16_bf16 v[64:79], v[196:199], v[200:203], v[64:79]
	ds_read_b128 v[192:195], v169
	ds_read_b128 v[196:199], v169 offset:4096
	ds_read_b128 v[200:203], v148 offset:2048
	s_waitcnt lgkmcnt(0)
	v_mfma_f32_32x32x16_bf16 v[80:95], v[192:195], v[200:203], v[80:95]
	v_mfma_f32_32x32x16_bf16 v[64:79], v[196:199], v[200:203], v[64:79]
	ds_read_b128 v[192:195], v171
	ds_read_b128 v[196:199], v171 offset:4096
	ds_read_b128 v[200:203], v148 offset:3072
	s_waitcnt lgkmcnt(0)
	v_mfma_f32_32x32x16_bf16 v[80:95], v[192:195], v[200:203], v[80:95]
	v_exp_f32_e32 v192, v188
	v_add_f32_e32 v188, 0, v108
	v_add_f32_e32 v188, v123, v188
	v_add_f32_e32 v188, v109, v188
	v_add_f32_e32 v188, v122, v188
	v_add_f32_e32 v188, v110, v188
	v_add_f32_e32 v188, v121, v188
	v_add_f32_e32 v188, v111, v188
	v_add_f32_e32 v188, v120, v188
	v_add_f32_e32 v188, v112, v188
	v_add_f32_e32 v188, v119, v188
	v_add_f32_e32 v188, v113, v188
	v_add_f32_e32 v188, v118, v188
	v_add_f32_e32 v188, v114, v188
	v_add_f32_e32 v188, v117, v188
	v_add_f32_e32 v188, v115, v188
	v_add_f32_e32 v188, v116, v188
	v_add_f32_e32 v188, v192, v188
	v_add_f32_e32 v188, v130, v188
	v_add_f32_e32 v188, v131, v188
	v_add_f32_e32 v188, v183, v188
	v_add_f32_e32 v188, v184, v188
	v_add_f32_e32 v188, v185, v188
	v_add_f32_e32 v188, v186, v188
	v_add_f32_e32 v188, v187, v188
	v_add_f32_e32 v188, v125, v188
	v_exp_f32_e32 v193, v190
	v_add_f32_e32 v188, v126, v188
	v_mfma_f32_32x32x16_bf16 v[64:79], v[196:199], v[200:203], v[64:79]
	v_add_f32_e32 v188, v127, v188
	v_add_f32_e32 v188, v128, v188
	v_add_f32_e32 v188, v129, v188
	v_add_f32_e32 v188, v193, v188
	v_add_f32_e32 v188, v191, v188
	v_add_f32_e32 v188, v124, v188
	v_mov_b32_e32 v190, v188
	s_nop 1
	v_permlane32_swap_b32_e32 v188, v190
	v_cvt_pk_bf16_f32 v108, v108, v123
	v_cvt_pk_bf16_f32 v109, v109, v122
	v_cvt_pk_bf16_f32 v110, v110, v121
	v_cvt_pk_bf16_f32 v111, v111, v120
	v_cvt_pk_bf16_f32 v112, v112, v119
	v_cvt_pk_bf16_f32 v113, v113, v118
	v_cvt_pk_bf16_f32 v114, v114, v117
	v_cvt_pk_bf16_f32 v115, v115, v116
	v_cvt_pk_bf16_f32 v116, v192, v130
	v_cvt_pk_bf16_f32 v117, v131, v183
	v_cvt_pk_bf16_f32 v118, v184, v185
	v_cvt_pk_bf16_f32 v119, v186, v187
	v_cvt_pk_bf16_f32 v120, v125, v126
	v_cvt_pk_bf16_f32 v121, v127, v128
	v_cvt_pk_bf16_f32 v122, v129, v193
	v_cvt_pk_bf16_f32 v123, v191, v124
	s_nop 0
	v_permlane32_swap_b32_e32 v108, v110
	v_permlane32_swap_b32_e32 v109, v111
	v_permlane32_swap_b32_e32 v112, v114
	v_permlane32_swap_b32_e32 v113, v115
	v_permlane32_swap_b32_e32 v116, v118
	v_permlane32_swap_b32_e32 v117, v119
	v_permlane32_swap_b32_e32 v120, v122
	v_permlane32_swap_b32_e32 v121, v123
	s_mov_b32 s0, 0x6e60000
	v_add_co_u32_e32 v124, vcc, s0, v140
	s_mov_b32 s0, 0x6e70000
	s_nop 0
	v_addc_co_u32_e32 v125, vcc, 0, v141, vcc
	v_add_co_u32_e32 v128, vcc, s0, v140
	s_mov_b32 s0, 0x4a60000
	s_nop 0
	v_addc_co_u32_e32 v129, vcc, 0, v141, vcc
	v_add_co_u32_e32 v184, vcc, s0, v140
	s_mov_b32 s0, 0x4a70000
	s_nop 0
	v_addc_co_u32_e32 v185, vcc, 0, v141, vcc
	v_add_co_u32_e32 v140, vcc, s0, v140
	s_mov_b32 s0, 0x11506000
	s_nop 0
	v_addc_co_u32_e32 v141, vcc, 0, v141, vcc
	global_load_dwordx4 v[124:127], v[124:125], off
	s_nop 0
	global_load_dwordx4 v[128:131], v[128:129], off
	s_nop 0
	global_load_dwordx4 v[184:187], v[184:185], off
	s_nop 0
	global_load_dwordx4 v[192:195], v[140:141], off
	v_add_co_u32_e32 v140, vcc, s0, v142
	s_nop 1
	v_addc_co_u32_e32 v141, vcc, 0, v143, vcc
	global_load_dwordx4 v[196:199], v[140:141], off
	ds_read_b64_tr_b16 v[140:141], v149 offset:0
	ds_read_b64_tr_b16 v[142:143], v149 offset:0x800
	ds_read_b64_tr_b16 v[200:201], v149 offset:0x1000
	ds_read_b64_tr_b16 v[202:203], v149 offset:0x1800
	ds_read_b64_tr_b16 v[204:205], v149 offset:0x2000
	ds_read_b64_tr_b16 v[206:207], v149 offset:0x2800
	ds_read_b64_tr_b16 v[208:209], v149 offset:0x3000
	ds_read_b64_tr_b16 v[210:211], v149 offset:0x3800
	s_nop 0
	s_waitcnt lgkmcnt(6)
	v_mfma_f32_32x32x16_bf16 v[0:15], v[108:111], v[140:143], v[0:15]
	v_max_f32_e32 v140, v81, v81
	v_max_f32_e32 v141, v80, v80
	v_max_f32_e32 v140, v141, v140
	v_max3_f32 v140, v140, v82, v83
	v_max3_f32 v140, v140, v84, v85
	v_max3_f32 v140, v140, v86, v87
	v_max3_f32 v140, v140, v88, v89
	s_waitcnt lgkmcnt(4)
; __device__ __forceinline__ void pv_sm(f32x16* o, int vb, bf16x8 pa0, bf16x8 pa1, bf16x8 pa2, bf16x8 pa3, f32x16& p0, f32x16& p1, float& m_reg, float& mn, float& alpha, const float SCALE) {
;   const float C = SCALE * 1.4426950408889634f;
;   pv_one<0>(o[0], vb, pa0, pa1, pa2, pa3);
;   float pmax = p0[0];
; #pragma unroll
;   for (int r = 1; r < 16; ++r) pmax = fmaxf(pmax, p0[r]);
;   pv_one<1>(o[1], vb, pa0, pa1, pa2, pa3);
; #pragma unroll
;   for (int r = 0; r < 16; ++r) pmax = fmaxf(pmax, p1[r]);
;   { auto rr = __builtin_amdgcn_permlane32_swap(__float_as_uint(pmax), __float_as_uint(pmax), false, false);
;     pmax = fmaxf(__uint_as_float(rr[0]), __uint_as_float(rr[1])); }
;   if (__builtin_expect(__all(pmax - m_reg <= THR / SCALE), 1)) { mn = m_reg; alpha = 1.f; }
;   else { mn = fmaxf(m_reg, pmax); alpha = __builtin_amdgcn_exp2f((m_reg - mn) * C); m_reg = mn; }
;   const float mnC = -mn * C;
;   pv_one<2>(o[2], vb, pa0, pa1, pa2, pa3);
; #pragma unroll
;   for (int r = 0; r < 16; ++r) p0[r] = fmaf(p0[r], C, mnC);
; #pragma unroll
;   for (int r = 0; r < 16; ++r) p1[r] = fmaf(p1[r], C, mnC);
;   pv_one<3>(o[3], vb, pa0, pa1, pa2, pa3);
; #pragma unroll
;   for (int r = 0; r < 16; ++r) p0[r] = __builtin_amdgcn_exp2f(p0[r]);
; }
	v_mfma_f32_32x32x16_bf16 v[0:15], v[112:115], v[200:203], v[0:15]
	v_max3_f32 v140, v140, v90, v91
	v_max3_f32 v140, v140, v92, v93
	v_max3_f32 v183, v140, v94, v95
	ds_read_b64_tr_b16 v[140:141], v149 offset:0x200
	ds_read_b64_tr_b16 v[142:143], v149 offset:0xa00
	ds_read_b64_tr_b16 v[200:201], v149 offset:0x1200
	ds_read_b64_tr_b16 v[202:203], v149 offset:0x1a00
	s_waitcnt lgkmcnt(6)
	v_mfma_f32_32x32x16_bf16 v[0:15], v[116:119], v[204:207], v[0:15]
	ds_read_b64_tr_b16 v[204:205], v149 offset:0x2200
	ds_read_b64_tr_b16 v[206:207], v149 offset:0x2a00
	s_waitcnt lgkmcnt(6)
	v_mfma_f32_32x32x16_bf16 v[0:15], v[120:123], v[208:211], v[0:15]
	ds_read_b64_tr_b16 v[208:209], v149 offset:0x3200
	ds_read_b64_tr_b16 v[210:211], v149 offset:0x3a00
	s_waitcnt lgkmcnt(6)
	v_mfma_f32_32x32x16_bf16 v[48:63], v[108:111], v[140:143], v[48:63]
	v_max3_f32 v183, v183, v64, v65
	v_max3_f32 v183, v183, v66, v67
	v_max3_f32 v183, v183, v68, v69
	v_max3_f32 v183, v183, v70, v71
	v_max3_f32 v183, v183, v72, v73
	v_max3_f32 v183, v183, v74, v75
	v_max3_f32 v140, v183, v76, v77
	s_waitcnt lgkmcnt(4)
	v_mfma_f32_32x32x16_bf16 v[48:63], v[112:115], v[200:203], v[48:63]
	v_max3_f32 v140, v140, v78, v79
	v_mov_b32_e32 v141, v140
	s_nop 1
	v_permlane32_swap_b32_e32 v140, v141
	ds_read_b64_tr_b16 v[200:201], v149 offset:0x400
	v_max_f32_e32 v141, v141, v141
	v_max_f32_e32 v140, v140, v140
	s_waitcnt lgkmcnt(3)
	v_mfma_f32_32x32x16_bf16 v[48:63], v[116:119], v[204:207], v[48:63]
	ds_read_b64_tr_b16 v[202:203], v149 offset:0xc00
	v_max_f32_e32 v140, v140, v141
	v_max_f32_e32 v141, v175, v175
	ds_read_b64_tr_b16 v[204:205], v149 offset:0x1400
	v_max_f32_e32 v141, v141, v140
	ds_read_b64_tr_b16 v[206:207], v149 offset:0x1c00
	v_sub_f32_e32 v142, v140, v175
	s_waitcnt lgkmcnt(4)
	v_mfma_f32_32x32x16_bf16 v[48:63], v[120:123], v[208:211], v[48:63]
	v_sub_f32_e32 v140, v175, v141
	ds_read_b64_tr_b16 v[208:209], v149 offset:0x2400
	v_mul_f32_e32 v140, 0x3dd53b94, v140
	ds_read_b64_tr_b16 v[210:211], v149 offset:0x2c00
	v_exp_f32_e32 v140, v140
	ds_read_b64_tr_b16 v[214:215], v149 offset:0x3400
	v_cmp_ge_f32_e32 vcc, s82, v142
	ds_read_b64_tr_b16 v[216:217], v149 offset:0x3c00
	s_cmp_eq_u64 vcc, exec
	s_cselect_b64 s[4:5], -1, 0
	v_cndmask_b32_e64 v140, v140, 1.0, s[4:5]
	s_waitcnt lgkmcnt(6)
	v_mfma_f32_32x32x16_bf16 v[32:47], v[108:111], v[200:203], v[32:47]
	ds_read_b64_tr_b16 v[200:201], v149 offset:0x600
	ds_read_b64_tr_b16 v[202:203], v149 offset:0xe00
	s_waitcnt lgkmcnt(6)
	v_mfma_f32_32x32x16_bf16 v[32:47], v[112:115], v[204:207], v[32:47]
	ds_read_b64_tr_b16 v[204:205], v149 offset:0x1600
	ds_read_b64_tr_b16 v[206:207], v149 offset:0x1e00
	s_waitcnt lgkmcnt(6)
	v_mfma_f32_32x32x16_bf16 v[32:47], v[116:119], v[208:211], v[32:47]
	ds_read_b64_tr_b16 v[208:209], v149 offset:0x2600
	ds_read_b64_tr_b16 v[210:211], v149 offset:0x2e00
	s_waitcnt lgkmcnt(6)
	v_mfma_f32_32x32x16_bf16 v[32:47], v[120:123], v[214:217], v[32:47]
	ds_read_b64_tr_b16 v[214:215], v149 offset:0x3600
	ds_read_b64_tr_b16 v[216:217], v149 offset:0x3e00
	s_waitcnt lgkmcnt(6)
	v_mfma_f32_32x32x16_bf16 v[16:31], v[108:111], v[200:203], v[16:31]
	s_waitcnt lgkmcnt(0)
	s_barrier
	s_waitcnt vmcnt(0)
	v_cmp_gt_f32_e32 vcc, 1.0, v140
	s_waitcnt vmcnt(4)
	ds_write_b128 v155, v[124:127] offset:16384
	s_waitcnt vmcnt(3)
	ds_write_b128 v156, v[128:131] offset:16384
	s_waitcnt vmcnt(2)
	ds_write_b128 v153, v[184:187] offset:49152
	s_waitcnt vmcnt(1)
	ds_write_b128 v154, v[192:195] offset:49152
	s_waitcnt vmcnt(0)
	ds_write_b128 v174, v[196:199]
	v_mfma_f32_32x32x16_bf16 v[16:31], v[112:115], v[204:207], v[16:31]
	v_mfma_f32_32x32x16_bf16 v[16:31], v[116:119], v[208:211], v[16:31]
	v_mfma_f32_32x32x16_bf16 v[16:31], v[120:123], v[214:217], v[16:31]
	s_cbranch_vccz .LBB0_605
	s_and_saveexec_b64 s[0:1], s[2:3]
	ds_write_b32 v147, v140 offset:128
	s_or_b64 exec, exec, s[0:1]
	s_waitcnt lgkmcnt(0)
	v_add_u32_e32 v120, v135, v132
	ds_read_b128 v[108:111], v120 offset:224
	ds_read_b128 v[112:115], v120 offset:192
	ds_read_b128 v[116:119], v120 offset:160
	ds_read_b128 v[120:123], v120 offset:128
	s_waitcnt lgkmcnt(3)
	v_pk_mul_f32 v[12:13], v[12:13], v[108:109]
	s_waitcnt lgkmcnt(2)
	v_pk_mul_f32 v[8:9], v[8:9], v[112:113]
	s_waitcnt lgkmcnt(1)
	v_pk_mul_f32 v[4:5], v[4:5], v[116:117]
	v_pk_mul_f32 v[14:15], v[14:15], v[110:111]
	v_pk_mul_f32 v[10:11], v[10:11], v[114:115]
	v_pk_mul_f32 v[6:7], v[6:7], v[118:119]
	s_waitcnt lgkmcnt(0)
	v_pk_mul_f32 v[2:3], v[2:3], v[122:123]
	v_pk_mul_f32 v[0:1], v[0:1], v[120:121]
	v_pk_mul_f32 v[60:61], v[60:61], v[108:109]
	v_pk_mul_f32 v[56:57], v[56:57], v[112:113]
	v_pk_mul_f32 v[52:53], v[52:53], v[116:117]
	v_pk_mul_f32 v[62:63], v[62:63], v[110:111]
	v_pk_mul_f32 v[58:59], v[58:59], v[114:115]
	v_pk_mul_f32 v[54:55], v[54:55], v[118:119]
	v_pk_mul_f32 v[50:51], v[50:51], v[122:123]
	v_pk_mul_f32 v[48:49], v[48:49], v[120:121]
	v_pk_mul_f32 v[44:45], v[44:45], v[108:109]
	v_pk_mul_f32 v[40:41], v[40:41], v[112:113]
	v_pk_mul_f32 v[36:37], v[36:37], v[116:117]
	v_pk_mul_f32 v[46:47], v[46:47], v[110:111]
	v_pk_mul_f32 v[42:43], v[42:43], v[114:115]
	v_pk_mul_f32 v[38:39], v[38:39], v[118:119]
	v_pk_mul_f32 v[34:35], v[34:35], v[122:123]
	v_pk_mul_f32 v[32:33], v[32:33], v[120:121]
	v_pk_mul_f32 v[28:29], v[28:29], v[108:109]
	v_pk_mul_f32 v[24:25], v[24:25], v[112:113]
	v_pk_mul_f32 v[20:21], v[20:21], v[116:117]
	v_pk_mul_f32 v[30:31], v[30:31], v[110:111]
	v_pk_mul_f32 v[26:27], v[26:27], v[114:115]
	v_pk_mul_f32 v[22:23], v[22:23], v[118:119]
	v_pk_mul_f32 v[18:19], v[18:19], v[122:123]
	v_pk_mul_f32 v[16:17], v[16:17], v[120:121]

; #define SBAR() __builtin_amdgcn_sched_barrier(0)
; __device__ __forceinline__ void finishSM(f32x16& p0, f32x16& p1, float alpha, float& l_reg, bf16x8& pa0, bf16x8& pa1, bf16x8& pa2, bf16x8& pa3) {
; #pragma unroll
;   for (int r = 0; r < 16; ++r) p1[r] = __builtin_amdgcn_exp2f(p1[r]);
;   float ps = 0;
; #pragma unroll
;   for (int r = 0; r < 16; ++r) ps += p0[r];
; #pragma unroll
;   for (int r = 0; r < 16; ++r) ps += p1[r];
;   { auto rr = __builtin_amdgcn_permlane32_swap(__float_as_uint(ps), __float_as_uint(ps), false, false);
;     ps = __uint_as_float(rr[0]) + __uint_as_float(rr[1]); }
;   l_reg = l_reg * alpha + ps;
;     ...
;   PK4(p0, 0, pa0); PK4(p0, 8, pa1); PK4(p1, 0, pa2); PK4(p1, 8, pa3);
;     ...
; }
; template <int DKR, int NQ>
; __device__ __forceinline__ void qkt(f32x16& p0, f32x16& p1, const char* Ks, const char* Krs, const char* Qrs, const bf16x8* qr, int r32, int hi, int lane) {
;   p0 = f32x16{}; p1 = f32x16{};
; #pragma unroll
;   for (int d0 = 0; d0 < 8; ++d0) { int cb = (d0 * 16 + hi * 8) * 2;
;     bf16x8 b0 = *reinterpret_cast<const bf16x8*>(Ks + KSWZ(r32, cb));
;     bf16x8 b1 = *reinterpret_cast<const bf16x8*>(Ks + KSWZ(32 + r32, cb));
;     bf16x8 qf;
;     if (d0 >= 8 - NQ) qf = *reinterpret_cast<const bf16x8*>(Qrs + (d0 - (8 - NQ) + 4) * 1024 + lane * 16); else qf = qr[d0];
;     p0 = __builtin_amdgcn_mfma_f32_32x32x16_bf16(b0, qf, p0, 0, 0, 0);
;     p1 = __builtin_amdgcn_mfma_f32_32x32x16_bf16(b1, qf, p1, 0, 0, 0); }
;   if constexpr (DKR > 0) {
;     SBAR();
; #pragma unroll
;     for (int d0 = 0; d0 < DKR / 16; ++d0) { int cb = (d0 * 16 + hi * 8) * 2;
;       bf16x8 b0 = *reinterpret_cast<const bf16x8*>(Krs + KRSWZ(r32, cb));
;       bf16x8 b1 = *reinterpret_cast<const bf16x8*>(Krs + KRSWZ(32 + r32, cb));
;       bf16x8 qf = *reinterpret_cast<const bf16x8*>(Qrs + d0 * 1024 + lane * 16);
;       p0 = __builtin_amdgcn_mfma_f32_32x32x16_bf16(b0, qf, p0, 0, 0, 0);
;       p1 = __builtin_amdgcn_mfma_f32_32x32x16_bf16(b1, qf, p1, 0, 0, 0); }
;   }
; }
.LBB0_616:
	ds_read_b128 v[64:67], v194 offset:49152
	ds_read_b128 v[68:71], v194 offset:57344
	ds_read_b128 v[204:207], v200 offset:49152
	ds_read_b128 v[208:211], v200 offset:57344
	ds_read_b128 v[232:235], v201 offset:49152
	ds_read_b128 v[236:239], v201 offset:57344
	ds_read_b128 v[248:251], v195 offset:49152
	ds_read_b128 v[252:255], v195 offset:57344
	v_exp_f32_e32 v156, v156
	v_exp_f32_e32 v157, v157
	s_waitcnt lgkmcnt(7)
	v_mfma_f32_32x32x16_bf16 v[80:95], v[64:67], v[124:127], 0
	v_exp_f32_e32 v154, v154
	v_exp_f32_e32 v155, v155
	v_exp_f32_e32 v148, v148
	v_exp_f32_e32 v149, v149
	v_exp_f32_e32 v146, v146
	v_exp_f32_e32 v147, v147
	v_exp_f32_e32 v144, v144
	s_waitcnt lgkmcnt(6)
	v_mfma_f32_32x32x16_bf16 v[64:79], v[68:71], v[124:127], 0
	v_exp_f32_e32 v145, v145
	v_exp_f32_e32 v158, v158
	v_exp_f32_e32 v159, v159
	v_exp_f32_e32 v152, v152
	v_exp_f32_e32 v153, v153
	v_exp_f32_e32 v150, v150
	v_exp_f32_e32 v151, v151
	s_waitcnt lgkmcnt(5)
	v_mfma_f32_32x32x16_bf16 v[80:95], v[204:207], v[120:123], v[80:95]
	ds_read_b128 v[204:207], v196 offset:49152
	s_waitcnt lgkmcnt(5)
	v_mfma_f32_32x32x16_bf16 v[64:79], v[208:211], v[120:123], v[64:79]
	ds_read_b128 v[208:211], v196 offset:57344
	s_waitcnt lgkmcnt(5)
	v_mfma_f32_32x32x16_bf16 v[80:95], v[232:235], v[116:119], v[80:95]
	ds_read_b128 v[232:235], v197 offset:49152
	s_waitcnt lgkmcnt(5)
	v_mfma_f32_32x32x16_bf16 v[64:79], v[236:239], v[116:119], v[64:79]
	ds_read_b128 v[236:239], v197 offset:57344
	s_waitcnt lgkmcnt(5)
	v_mfma_f32_32x32x16_bf16 v[80:95], v[248:251], v[112:115], v[80:95]
	ds_read_b128 v[248:251], v198 offset:49152
	s_waitcnt lgkmcnt(5)
	v_mfma_f32_32x32x16_bf16 v[64:79], v[252:255], v[112:115], v[64:79]
	ds_read_b128 v[252:255], v198 offset:57344
	s_waitcnt lgkmcnt(5)
	v_mfma_f32_32x32x16_bf16 v[80:95], v[204:207], v[108:111], v[80:95]
	ds_read_b128 v[204:207], v199 offset:49152
	s_waitcnt lgkmcnt(5)
	v_mfma_f32_32x32x16_bf16 v[64:79], v[208:211], v[108:111], v[64:79]
	ds_read_b128 v[208:211], v199 offset:57344
	s_waitcnt lgkmcnt(5)
	v_mfma_f32_32x32x16_bf16 v[80:95], v[232:235], v[104:107], v[80:95]
	s_waitcnt lgkmcnt(4)
	v_mfma_f32_32x32x16_bf16 v[64:79], v[236:239], v[104:107], v[64:79]
	s_waitcnt lgkmcnt(3)
	v_mfma_f32_32x32x16_bf16 v[80:95], v[248:251], v[100:103], v[80:95]
	s_waitcnt lgkmcnt(2)
	v_mfma_f32_32x32x16_bf16 v[64:79], v[252:255], v[100:103], v[64:79]
	s_waitcnt lgkmcnt(1)
	v_mfma_f32_32x32x16_bf16 v[80:95], v[204:207], v[96:99], v[80:95]
	v_add_f32_e32 v204, 0, v160
	v_add_f32_e32 v204, v175, v204
	v_add_f32_e32 v204, v161, v204
	v_add_f32_e32 v204, v174, v204
	v_add_f32_e32 v204, v162, v204
	v_add_f32_e32 v204, v173, v204
	v_add_f32_e32 v204, v163, v204
	v_add_f32_e32 v204, v172, v204
	v_add_f32_e32 v204, v164, v204
	v_add_f32_e32 v204, v171, v204
	v_add_f32_e32 v204, v165, v204
	v_add_f32_e32 v204, v170, v204
	v_add_f32_e32 v204, v166, v204
	v_add_f32_e32 v204, v169, v204
	v_add_f32_e32 v204, v167, v204
	v_add_f32_e32 v204, v168, v204
	v_add_f32_e32 v204, v156, v204
	v_add_f32_e32 v204, v157, v204
	v_add_f32_e32 v204, v154, v204
	v_add_f32_e32 v204, v155, v204
	v_add_f32_e32 v204, v148, v204
	v_add_f32_e32 v204, v149, v204
	v_add_f32_e32 v204, v146, v204
	v_add_f32_e32 v204, v147, v204
	v_add_f32_e32 v204, v144, v204
	v_add_f32_e32 v204, v145, v204
	s_waitcnt lgkmcnt(0)
	v_mfma_f32_32x32x16_bf16 v[64:79], v[208:211], v[96:99], v[64:79]
	v_add_f32_e32 v204, v158, v204
	v_add_f32_e32 v204, v159, v204
	v_add_f32_e32 v204, v152, v204
	v_add_f32_e32 v204, v153, v204
	v_add_f32_e32 v204, v150, v204
	v_add_f32_e32 v205, v151, v204
	v_mov_b32_e32 v206, v205
	s_nop 1
	v_permlane32_swap_b32_e32 v205, v206
	v_cvt_pk_bf16_f32 v160, v160, v175
	v_cvt_pk_bf16_f32 v161, v161, v174
	v_cvt_pk_bf16_f32 v162, v162, v173
	v_cvt_pk_bf16_f32 v163, v163, v172
	v_cvt_pk_bf16_f32 v164, v164, v171
	v_cvt_pk_bf16_f32 v165, v165, v170
	v_cvt_pk_bf16_f32 v166, v166, v169
	v_cvt_pk_bf16_f32 v167, v167, v168
	v_cvt_pk_bf16_f32 v168, v156, v157
	v_cvt_pk_bf16_f32 v169, v154, v155
	v_cvt_pk_bf16_f32 v170, v148, v149
	v_cvt_pk_bf16_f32 v171, v146, v147
	v_cvt_pk_bf16_f32 v172, v144, v145
	v_cvt_pk_bf16_f32 v173, v158, v159
	v_cvt_pk_bf16_f32 v174, v152, v153
	v_cvt_pk_bf16_f32 v175, v150, v151
	s_nop 0
	v_permlane32_swap_b32_e32 v160, v162
	v_permlane32_swap_b32_e32 v161, v163
	v_permlane32_swap_b32_e32 v164, v166
	v_permlane32_swap_b32_e32 v165, v167
	v_permlane32_swap_b32_e32 v168, v170
	v_permlane32_swap_b32_e32 v169, v171
	v_permlane32_swap_b32_e32 v172, v174
	v_permlane32_swap_b32_e32 v173, v175
	s_mov_b32 s0, 0xffff4000
	v_add_co_u32_e32 v144, vcc, s0, v180
	s_movk_i32 s0, 0x8000
	s_nop 0
	v_addc_co_u32_e32 v145, vcc, -1, v181, vcc
	v_add_co_u32_e32 v148, vcc, s0, v180
	s_mov_b32 s0, 0xff6f4000
	s_nop 0
	v_addc_co_u32_e32 v149, vcc, -1, v181, vcc
	v_add_co_u32_e32 v152, vcc, s0, v180
	s_mov_b32 s0, 0xff6f8000
	s_nop 0
	v_addc_co_u32_e32 v153, vcc, -1, v181, vcc
	v_add_co_u32_e32 v156, vcc, s0, v180
	global_load_dwordx4 v[144:147], v[144:145], off
	s_nop 0
	global_load_dwordx4 v[148:151], v[148:149], off
	v_addc_co_u32_e32 v157, vcc, -1, v181, vcc
	global_load_dwordx4 v[152:155], v[152:153], off
	s_nop 0
	global_load_dwordx4 v[156:159], v[156:157], off
	ds_read_b64_tr_b16 v[208:209], v188 offset:0
	ds_read_b64_tr_b16 v[210:211], v188 offset:0x800
	ds_read_b64_tr_b16 v[214:215], v188 offset:0x1000
	ds_read_b64_tr_b16 v[216:217], v188 offset:0x1800
	ds_read_b64_tr_b16 v[218:219], v188 offset:0x2000
	ds_read_b64_tr_b16 v[220:221], v188 offset:0x2800
	ds_read_b64_tr_b16 v[222:223], v188 offset:0x3000
	ds_read_b64_tr_b16 v[224:225], v188 offset:0x3800
	s_nop 0
	s_waitcnt lgkmcnt(6)
; __device__ __forceinline__ void pv_sm(f32x16* o, int vb, bf16x8 pa0, bf16x8 pa1, bf16x8 pa2, bf16x8 pa3, f32x16& p0, f32x16& p1, float& m_reg, float& mn, float& alpha, const float SCALE) {
;   const float C = SCALE * 1.4426950408889634f;
;   pv_one<0>(o[0], vb, pa0, pa1, pa2, pa3);
;   float pmax = p0[0];
; #pragma unroll
;   for (int r = 1; r < 16; ++r) pmax = fmaxf(pmax, p0[r]);
;   pv_one<1>(o[1], vb, pa0, pa1, pa2, pa3);
; #pragma unroll
;   for (int r = 0; r < 16; ++r) pmax = fmaxf(pmax, p1[r]);
;   { auto rr = __builtin_amdgcn_permlane32_swap(__float_as_uint(pmax), __float_as_uint(pmax), false, false);
;     pmax = fmaxf(__uint_as_float(rr[0]), __uint_as_float(rr[1])); }
;   if (__builtin_expect(__all(pmax - m_reg <= THR / SCALE), 1)) { mn = m_reg; alpha = 1.f; }
;   else { mn = fmaxf(m_reg, pmax); alpha = __builtin_amdgcn_exp2f((m_reg - mn) * C); m_reg = mn; }
;   const float mnC = -mn * C;
;   pv_one<2>(o[2], vb, pa0, pa1, pa2, pa3);
; #pragma unroll
;   for (int r = 0; r < 16; ++r) p0[r] = fmaf(p0[r], C, mnC);
; #pragma unroll
;   for (int r = 0; r < 16; ++r) p1[r] = fmaf(p1[r], C, mnC);
;   pv_one<3>(o[3], vb, pa0, pa1, pa2, pa3);
; #pragma unroll
;   for (int r = 0; r < 16; ++r) p0[r] = __builtin_amdgcn_exp2f(p0[r]);
; }
	v_mfma_f32_32x32x16_bf16 v[0:15], v[160:163], v[208:211], v[0:15]
	ds_read_b64_tr_b16 v[208:209], v188 offset:0x200
	ds_read_b64_tr_b16 v[210:211], v188 offset:0xa00
	v_max_f32_e32 v204, v81, v81
	v_max_f32_e32 v207, v80, v80
	v_max_f32_e32 v204, v207, v204
	v_max3_f32 v204, v204, v82, v83
	v_max3_f32 v204, v204, v84, v85
	s_waitcnt lgkmcnt(6)
	v_mfma_f32_32x32x16_bf16 v[0:15], v[164:167], v[214:217], v[0:15]
	ds_read_b64_tr_b16 v[214:215], v188 offset:0x1200
	ds_read_b64_tr_b16 v[216:217], v188 offset:0x1a00
	v_max3_f32 v204, v204, v86, v87
	v_max3_f32 v204, v204, v88, v89
	v_max3_f32 v204, v204, v90, v91
	v_max3_f32 v204, v204, v92, v93
	v_max3_f32 v204, v204, v94, v95
	s_waitcnt lgkmcnt(6)
	v_mfma_f32_32x32x16_bf16 v[0:15], v[168:171], v[218:221], v[0:15]
	ds_read_b64_tr_b16 v[218:219], v188 offset:0x2200
	ds_read_b64_tr_b16 v[220:221], v188 offset:0x2a00
	ds_read_b64_tr_b16 v[226:227], v188 offset:0x3200
	ds_read_b64_tr_b16 v[228:229], v188 offset:0x3a00
	s_waitcnt lgkmcnt(8)
	v_mfma_f32_32x32x16_bf16 v[0:15], v[172:175], v[222:225], v[0:15]
	s_waitcnt lgkmcnt(6)
	v_mfma_f32_32x32x16_bf16 v[48:63], v[160:163], v[208:211], v[48:63]
	v_max3_f32 v204, v204, v64, v65
	v_max3_f32 v204, v204, v66, v67
	v_max3_f32 v204, v204, v68, v69
	v_max3_f32 v204, v204, v70, v71
	v_max3_f32 v204, v204, v72, v73
	v_max3_f32 v204, v204, v74, v75
	v_max3_f32 v204, v204, v76, v77
	s_waitcnt lgkmcnt(4)
	v_mfma_f32_32x32x16_bf16 v[48:63], v[164:167], v[214:217], v[48:63]
	v_max3_f32 v204, v204, v78, v79
	v_mov_b32_e32 v207, v204
	s_nop 1
	v_permlane32_swap_b32_e32 v204, v207
	v_max_f32_e32 v207, v207, v207
	v_max_f32_e32 v204, v204, v204
	v_max_f32_e32 v204, v204, v207
	v_max_f32_e32 v208, v203, v203
	v_sub_f32_e32 v207, v204, v203
	v_max_f32_e32 v204, v208, v204
	v_sub_f32_e32 v208, v203, v204
	v_mul_f32_e32 v208, 0x3e0293ee, v208
	s_waitcnt lgkmcnt(2)
	v_mfma_f32_32x32x16_bf16 v[48:63], v[168:171], v[218:221], v[48:63]
	v_exp_f32_e32 v208, v208
	v_cmp_ge_f32_e32 vcc, s47, v207
	s_cmp_eq_u64 vcc, exec
	s_cselect_b64 s[4:5], -1, 0
	v_cndmask_b32_e64 v207, v208, 1.0, s[4:5]
	ds_read_b64_tr_b16 v[208:209], v188 offset:0x400
	ds_read_b64_tr_b16 v[210:211], v188 offset:0xc00
	ds_read_b64_tr_b16 v[214:215], v188 offset:0x1400
	s_waitcnt lgkmcnt(3)
	v_mfma_f32_32x32x16_bf16 v[48:63], v[172:175], v[226:229], v[48:63]
	ds_read_b64_tr_b16 v[216:217], v188 offset:0x1c00
	ds_read_b64_tr_b16 v[218:219], v188 offset:0x2400
	ds_read_b64_tr_b16 v[220:221], v188 offset:0x2c00
	ds_read_b64_tr_b16 v[222:223], v188 offset:0x3400
	ds_read_b64_tr_b16 v[224:225], v188 offset:0x3c00
	s_waitcnt lgkmcnt(6)
	v_mfma_f32_32x32x16_bf16 v[32:47], v[160:163], v[208:211], v[32:47]
	ds_read_b64_tr_b16 v[208:209], v188 offset:0x600
	ds_read_b64_tr_b16 v[210:211], v188 offset:0xe00
	s_waitcnt lgkmcnt(6)
	v_mfma_f32_32x32x16_bf16 v[32:47], v[164:167], v[214:217], v[32:47]
	ds_read_b64_tr_b16 v[214:215], v188 offset:0x1600
	ds_read_b64_tr_b16 v[216:217], v188 offset:0x1e00
	s_waitcnt lgkmcnt(6)
	v_mfma_f32_32x32x16_bf16 v[32:47], v[168:171], v[218:221], v[32:47]
	ds_read_b64_tr_b16 v[218:219], v188 offset:0x2600
	ds_read_b64_tr_b16 v[220:221], v188 offset:0x2e00
	ds_read_b64_tr_b16 v[226:227], v188 offset:0x3600
	ds_read_b64_tr_b16 v[228:229], v188 offset:0x3e00
	s_waitcnt lgkmcnt(8)
	v_mfma_f32_32x32x16_bf16 v[32:47], v[172:175], v[222:225], v[32:47]
	s_waitcnt lgkmcnt(6)
	v_mfma_f32_32x32x16_bf16 v[16:31], v[160:163], v[208:211], v[16:31]
	s_waitcnt lgkmcnt(0)
	s_barrier
	s_waitcnt vmcnt(4)
	v_cmp_gt_f32_e32 vcc, 1.0, v207
	s_waitcnt vmcnt(4)
	ds_write_b128 v192, v[132:135]
	ds_write_b128 v193, v[140:143]
	ds_write_b128 v190, v[128:131] offset:32768
	ds_write_b128 v191, v[136:139] offset:32768
	v_mfma_f32_32x32x16_bf16 v[16:31], v[164:167], v[214:217], v[16:31]
	v_mfma_f32_32x32x16_bf16 v[16:31], v[168:171], v[218:221], v[16:31]
	v_mfma_f32_32x32x16_bf16 v[16:31], v[172:175], v[226:229], v[16:31]
	s_cbranch_vccz .LBB0_620
	s_and_saveexec_b64 s[0:1], s[2:3]
	ds_write_b32 v185, v207 offset:128
	s_or_b64 exec, exec, s[0:1]
	s_waitcnt lgkmcnt(0)
	v_add_u32_e32 v172, v179, v176
	ds_read_b128 v[160:163], v172 offset:224
	ds_read_b128 v[164:167], v172 offset:192
	ds_read_b128 v[168:171], v172 offset:160
	ds_read_b128 v[172:175], v172 offset:128
	s_waitcnt lgkmcnt(3)
	v_pk_mul_f32 v[12:13], v[12:13], v[160:161]
	s_waitcnt lgkmcnt(2)
	v_pk_mul_f32 v[8:9], v[8:9], v[164:165]
	s_waitcnt lgkmcnt(1)
	v_pk_mul_f32 v[4:5], v[4:5], v[168:169]
	v_pk_mul_f32 v[14:15], v[14:15], v[162:163]
	v_pk_mul_f32 v[10:11], v[10:11], v[166:167]
	v_pk_mul_f32 v[6:7], v[6:7], v[170:171]
	s_waitcnt lgkmcnt(0)
	v_pk_mul_f32 v[2:3], v[2:3], v[174:175]
	v_pk_mul_f32 v[0:1], v[0:1], v[172:173]
	v_pk_mul_f32 v[60:61], v[60:61], v[160:161]
	v_pk_mul_f32 v[56:57], v[56:57], v[164:165]
	v_pk_mul_f32 v[52:53], v[52:53], v[168:169]
	v_pk_mul_f32 v[62:63], v[62:63], v[162:163]
	v_pk_mul_f32 v[58:59], v[58:59], v[166:167]
	v_pk_mul_f32 v[54:55], v[54:55], v[170:171]
	v_pk_mul_f32 v[50:51], v[50:51], v[174:175]
	v_pk_mul_f32 v[48:49], v[48:49], v[172:173]
	v_pk_mul_f32 v[44:45], v[44:45], v[160:161]
	v_pk_mul_f32 v[40:41], v[40:41], v[164:165]
	v_pk_mul_f32 v[36:37], v[36:37], v[168:169]
	v_pk_mul_f32 v[46:47], v[46:47], v[162:163]
	v_pk_mul_f32 v[42:43], v[42:43], v[166:167]
	v_pk_mul_f32 v[38:39], v[38:39], v[170:171]
	v_pk_mul_f32 v[34:35], v[34:35], v[174:175]
	v_pk_mul_f32 v[32:33], v[32:33], v[172:173]
	v_pk_mul_f32 v[28:29], v[28:29], v[160:161]
	v_pk_mul_f32 v[24:25], v[24:25], v[164:165]
	v_pk_mul_f32 v[20:21], v[20:21], v[168:169]
	v_pk_mul_f32 v[30:31], v[30:31], v[162:163]
	v_pk_mul_f32 v[26:27], v[26:27], v[166:167]
	v_pk_mul_f32 v[22:23], v[22:23], v[170:171]
	v_pk_mul_f32 v[18:19], v[18:19], v[174:175]
	v_pk_mul_f32 v[16:17], v[16:17], v[172:173]

; __device__ __forceinline__ void pv_sm(f32x16* o, int vb, bf16x8 pa0, bf16x8 pa1, bf16x8 pa2, bf16x8 pa3, f32x16& p0, f32x16& p1, float& m_reg, float& mn, float& alpha, const float SCALE) {
;   const float C = SCALE * 1.4426950408889634f;
;   pv_one<0>(o[0], vb, pa0, pa1, pa2, pa3);
;   float pmax = p0[0];
; #pragma unroll
;   for (int r = 1; r < 16; ++r) pmax = fmaxf(pmax, p0[r]);
;   pv_one<1>(o[1], vb, pa0, pa1, pa2, pa3);
; #pragma unroll
;   for (int r = 0; r < 16; ++r) pmax = fmaxf(pmax, p1[r]);
;   { auto rr = __builtin_amdgcn_permlane32_swap(__float_as_uint(pmax), __float_as_uint(pmax), false, false);
;     pmax = fmaxf(__uint_as_float(rr[0]), __uint_as_float(rr[1])); }
;   if (__builtin_expect(__all(pmax - m_reg <= THR / SCALE), 1)) { mn = m_reg; alpha = 1.f; }
;   else { mn = fmaxf(m_reg, pmax); alpha = __builtin_amdgcn_exp2f((m_reg - mn) * C); m_reg = mn; }
;   const float mnC = -mn * C;
;   pv_one<2>(o[2], vb, pa0, pa1, pa2, pa3);
; #pragma unroll
;   for (int r = 0; r < 16; ++r) p0[r] = fmaf(p0[r], C, mnC);
; #pragma unroll
;   for (int r = 0; r < 16; ++r) p1[r] = fmaf(p1[r], C, mnC);
;   pv_one<3>(o[3], vb, pa0, pa1, pa2, pa3);
; #pragma unroll
;   for (int r = 0; r < 16; ++r) p0[r] = __builtin_amdgcn_exp2f(p0[r]);
; }
.LBB0_622:
	ds_read_b64_tr_b16 v[214:215], v186 offset:0
	ds_read_b64_tr_b16 v[216:217], v186 offset:0x800
	ds_read_b64_tr_b16 v[218:219], v186 offset:0x1000
	ds_read_b64_tr_b16 v[220:221], v186 offset:0x1800
	ds_read_b64_tr_b16 v[222:223], v186 offset:0x2000
	ds_read_b64_tr_b16 v[224:225], v186 offset:0x2800
	ds_read_b64_tr_b16 v[226:227], v186 offset:0x3000
	ds_read_b64_tr_b16 v[228:229], v186 offset:0x3800
	s_nop 0
	s_waitcnt lgkmcnt(6)
	v_mfma_f32_32x32x16_bf16 v[0:15], v[160:163], v[214:217], v[0:15]
	ds_read_b64_tr_b16 v[214:215], v186 offset:0x200
	ds_read_b64_tr_b16 v[216:217], v186 offset:0xa00
	v_max_f32_e32 v204, v81, v81
	v_max_f32_e32 v210, v80, v80
	v_max_f32_e32 v204, v210, v204
	v_max3_f32 v204, v204, v82, v83
	v_max3_f32 v204, v204, v84, v85
	s_waitcnt lgkmcnt(6)
	v_mfma_f32_32x32x16_bf16 v[0:15], v[164:167], v[218:221], v[0:15]
	ds_read_b64_tr_b16 v[218:219], v186 offset:0x1200
	ds_read_b64_tr_b16 v[220:221], v186 offset:0x1a00
	v_max3_f32 v204, v204, v86, v87
	v_max3_f32 v204, v204, v88, v89
	v_max3_f32 v204, v204, v90, v91
	v_max3_f32 v204, v204, v92, v93
	v_max3_f32 v204, v204, v94, v95
	s_waitcnt lgkmcnt(6)
	v_mfma_f32_32x32x16_bf16 v[0:15], v[168:171], v[222:225], v[0:15]
	ds_read_b64_tr_b16 v[222:223], v186 offset:0x2200
	ds_read_b64_tr_b16 v[224:225], v186 offset:0x2a00
	ds_read_b64_tr_b16 v[230:231], v186 offset:0x3200
	ds_read_b64_tr_b16 v[232:233], v186 offset:0x3a00
	s_waitcnt lgkmcnt(8)
	v_mfma_f32_32x32x16_bf16 v[0:15], v[172:175], v[226:229], v[0:15]
	s_waitcnt lgkmcnt(6)
	v_mfma_f32_32x32x16_bf16 v[48:63], v[160:163], v[214:217], v[48:63]
	v_max3_f32 v204, v204, v64, v65
	v_max3_f32 v204, v204, v66, v67
	v_max3_f32 v204, v204, v68, v69
	v_max3_f32 v204, v204, v70, v71
	v_max3_f32 v204, v204, v72, v73
	v_max3_f32 v204, v204, v74, v75
	v_max3_f32 v204, v204, v76, v77
	s_waitcnt lgkmcnt(4)
	v_mfma_f32_32x32x16_bf16 v[48:63], v[164:167], v[218:221], v[48:63]
	v_max3_f32 v204, v204, v78, v79
	v_mov_b32_e32 v210, v204
	s_nop 1
	v_permlane32_swap_b32_e32 v204, v210
	ds_read_b64_tr_b16 v[214:215], v186 offset:0x400
	v_max_f32_e32 v210, v210, v210
	v_max_f32_e32 v204, v204, v204
	s_waitcnt lgkmcnt(3)
	v_mfma_f32_32x32x16_bf16 v[48:63], v[168:171], v[222:225], v[48:63]
	ds_read_b64_tr_b16 v[216:217], v186 offset:0xc00
	v_max_f32_e32 v204, v204, v210
	v_max_f32_e32 v210, v203, v203
	ds_read_b64_tr_b16 v[218:219], v186 offset:0x1400
	v_max_f32_e32 v210, v210, v204
	ds_read_b64_tr_b16 v[220:221], v186 offset:0x1c00
	v_sub_f32_e32 v211, v204, v203
	s_waitcnt lgkmcnt(4)
	v_mfma_f32_32x32x16_bf16 v[48:63], v[172:175], v[230:233], v[48:63]
	v_sub_f32_e32 v204, v203, v210
	ds_read_b64_tr_b16 v[222:223], v186 offset:0x2400
	v_mul_f32_e32 v204, 0x3e0293ee, v204
	ds_read_b64_tr_b16 v[224:225], v186 offset:0x2c00
	v_exp_f32_e32 v204, v204
	ds_read_b64_tr_b16 v[226:227], v186 offset:0x3400
	v_cmp_ge_f32_e32 vcc, s47, v211
	ds_read_b64_tr_b16 v[228:229], v186 offset:0x3c00
	s_cmp_eq_u64 vcc, exec
	s_cselect_b64 s[4:5], -1, 0
	v_cndmask_b32_e64 v204, v204, 1.0, s[4:5]
	s_waitcnt lgkmcnt(6)
	v_mfma_f32_32x32x16_bf16 v[32:47], v[160:163], v[214:217], v[32:47]
	ds_read_b64_tr_b16 v[214:215], v186 offset:0x600
	ds_read_b64_tr_b16 v[216:217], v186 offset:0xe00
	s_waitcnt lgkmcnt(6)
	v_mfma_f32_32x32x16_bf16 v[32:47], v[164:167], v[218:221], v[32:47]
	ds_read_b64_tr_b16 v[218:219], v186 offset:0x1600
	ds_read_b64_tr_b16 v[220:221], v186 offset:0x1e00
	s_waitcnt lgkmcnt(6)
	v_mfma_f32_32x32x16_bf16 v[32:47], v[168:171], v[222:225], v[32:47]
	ds_read_b64_tr_b16 v[222:223], v186 offset:0x2600
	ds_read_b64_tr_b16 v[224:225], v186 offset:0x2e00
	s_waitcnt lgkmcnt(6)
	v_mfma_f32_32x32x16_bf16 v[32:47], v[172:175], v[226:229], v[32:47]
	ds_read_b64_tr_b16 v[226:227], v186 offset:0x3600
	ds_read_b64_tr_b16 v[228:229], v186 offset:0x3e00
	s_waitcnt lgkmcnt(6)
	v_mfma_f32_32x32x16_bf16 v[16:31], v[160:163], v[214:217], v[16:31]
	s_waitcnt lgkmcnt(0)
	s_barrier
	s_waitcnt vmcnt(4)
	v_cmp_gt_f32_e32 vcc, 1.0, v204
	s_waitcnt vmcnt(3)
	ds_write_b128 v192, v[144:147] offset:16384
	s_waitcnt vmcnt(2)
	ds_write_b128 v193, v[148:151] offset:16384
	s_waitcnt vmcnt(1)
	ds_write_b128 v190, v[152:155] offset:49152
	s_waitcnt vmcnt(0)
	ds_write_b128 v191, v[156:159] offset:49152
	v_mfma_f32_32x32x16_bf16 v[16:31], v[164:167], v[218:221], v[16:31]
	v_mfma_f32_32x32x16_bf16 v[16:31], v[168:171], v[222:225], v[16:31]
	v_mfma_f32_32x32x16_bf16 v[16:31], v[172:175], v[226:229], v[16:31]
	s_cbranch_vccz .LBB0_626
	s_and_saveexec_b64 s[0:1], s[2:3]
	ds_write_b32 v185, v204 offset:128
	s_or_b64 exec, exec, s[0:1]
	s_waitcnt lgkmcnt(0)
	v_add_u32_e32 v156, v179, v176
	ds_read_b128 v[144:147], v156 offset:224
	ds_read_b128 v[148:151], v156 offset:192
	ds_read_b128 v[152:155], v156 offset:160
	ds_read_b128 v[156:159], v156 offset:128
	s_waitcnt lgkmcnt(3)
	v_pk_mul_f32 v[12:13], v[12:13], v[144:145]
	s_waitcnt lgkmcnt(2)
	v_pk_mul_f32 v[8:9], v[8:9], v[148:149]
	s_waitcnt lgkmcnt(1)
	v_pk_mul_f32 v[4:5], v[4:5], v[152:153]
	v_pk_mul_f32 v[14:15], v[14:15], v[146:147]
	v_pk_mul_f32 v[10:11], v[10:11], v[150:151]
	v_pk_mul_f32 v[6:7], v[6:7], v[154:155]
	s_waitcnt lgkmcnt(0)
	v_pk_mul_f32 v[2:3], v[2:3], v[158:159]
	v_pk_mul_f32 v[0:1], v[0:1], v[156:157]
	v_pk_mul_f32 v[60:61], v[60:61], v[144:145]
	v_pk_mul_f32 v[56:57], v[56:57], v[148:149]
	v_pk_mul_f32 v[52:53], v[52:53], v[152:153]
	v_pk_mul_f32 v[62:63], v[62:63], v[146:147]
	v_pk_mul_f32 v[58:59], v[58:59], v[150:151]
	v_pk_mul_f32 v[54:55], v[54:55], v[154:155]
	v_pk_mul_f32 v[50:51], v[50:51], v[158:159]
	v_pk_mul_f32 v[48:49], v[48:49], v[156:157]
	v_pk_mul_f32 v[44:45], v[44:45], v[144:145]
	v_pk_mul_f32 v[40:41], v[40:41], v[148:149]
	v_pk_mul_f32 v[36:37], v[36:37], v[152:153]
	v_pk_mul_f32 v[46:47], v[46:47], v[146:147]
	v_pk_mul_f32 v[42:43], v[42:43], v[150:151]
	v_pk_mul_f32 v[38:39], v[38:39], v[154:155]
	v_pk_mul_f32 v[34:35], v[34:35], v[158:159]
	v_pk_mul_f32 v[32:33], v[32:33], v[156:157]
	v_pk_mul_f32 v[28:29], v[28:29], v[144:145]
	v_pk_mul_f32 v[24:25], v[24:25], v[148:149]
	v_pk_mul_f32 v[20:21], v[20:21], v[152:153]
	v_pk_mul_f32 v[30:31], v[30:31], v[146:147]
	v_pk_mul_f32 v[26:27], v[26:27], v[150:151]
	v_pk_mul_f32 v[22:23], v[22:23], v[154:155]
	v_pk_mul_f32 v[18:19], v[18:19], v[158:159]
	v_pk_mul_f32 v[16:17], v[16:17], v[156:157]
